# mlA wave-0 gate block: gate biases from an LDS table filled once per phase; the two 64-lane scans via DPP row shifts/broadcasts instead of 12 ds_bpermute round trips
# baseline (speedup 1.0000x reference)
.LBB0_733:
	v_and_b32_e32 v1, 31, v28
	v_ashrrev_i32_e32 v5, 7, v28
	v_lshl_or_b32 v6, v5, 5, v1
	v_mul_lo_u32 v6, v6, s20
	v_add_u32_e32 v33, 0xffffff00, v28
	v_and_b32_e32 v2, 63, v28
	v_lshl_add_u32 v32, v30, 2, 0
	v_add_u32_e32 v11, 0, v6
	v_lshrrev_b32_e32 v6, 1, v28
	s_movk_i32 s2, 0x8c
	v_lshlrev_b32_e32 v8, 2, v2
	v_ashrrev_i32_e32 v31, 31, v30
	v_and_or_b32 v1, v6, 32, v1
	v_mad_u64_u32 v[6:7], s[2:3], v30, s2, v[32:33]
	v_add_u32_e32 v42, 0, v8
	v_xor_b32_e32 v44, 4, v8
	v_xor_b32_e32 v45, 8, v8
	v_xor_b32_e32 v46, 16, v8
	v_lshl_add_u64 v[8:9], v[30:31], 2, s[88:89]
	s_mov_b64 s[2:3], 0x1fd00000
	v_lshl_add_u64 v[34:35], v[8:9], 0, s[2:3]
	v_lshlrev_b32_e32 v8, 2, v28
	v_add_u32_e32 v9, 0xfc, v8
	v_and_b32_e32 v31, 0xfc, v9
	v_add_u32_e32 v9, 0xf8, v8
	v_bfe_u32 v3, v28, 5, 1
	v_and_b32_e32 v47, 0xfc, v9
	v_add_u32_e32 v9, 0xf0, v8
	v_lshlrev_b32_e32 v12, 4, v3
	v_lshlrev_b32_e32 v5, 11, v5
	v_lshlrev_b32_e32 v3, 8, v3
	v_and_b32_e32 v48, 0xfc, v9
	v_add_u32_e32 v9, 0xe0, v8
	s_add_u32 s14, s88, 0x1fe30000
	v_lshlrev_b32_e32 v4, 3, v0
	v_lshlrev_b32_e32 v7, 4, v0
	v_cmp_eq_u32_e64 s[48:49], 0, v0
	v_and_b32_e32 v49, 0xfc, v9
	v_add_u32_e32 v9, 0xc0, v8
	v_xor_b32_e32 v51, 0x80, v8
	v_mad_u32_u24 v8, v0, s91, 0
	v_or3_b32 v0, v3, v5, v1
	v_readlane_b32 s2, v255, 23
	s_addc_u32 s15, s89, 0
	v_mad_u32_u24 v13, v1, s20, 0
	v_ashrrev_i32_e32 v1, 31, v0
	v_readlane_b32 s3, v255, 24
	s_add_u32 s16, s88, 0x1fe20000
	s_addc_u32 s17, s89, 0
	v_lshl_add_u64 v[36:37], v[0:1], 1, s[2:3]
	v_readlane_b32 s2, v253, 44
	v_lshlrev_b32_e32 v10, 1, v30
	s_lshl_b32 s2, s2, 6
	v_cmp_gt_u32_e64 s[44:45], 64, v28
	v_mov_b32_e32 v29, v113
	v_cmp_eq_u32_e64 s[46:47], 0, v2
	v_add_u32_e32 v43, 0xffffff00, v30
	v_cmp_gt_u32_e64 s[50:51], 2, v2
	v_cmp_gt_u32_e64 s[52:53], 4, v2
	v_cmp_gt_u32_e64 s[54:55], 8, v2
	v_and_b32_e32 v50, 0xfc, v9
	v_cmp_gt_u32_e64 s[56:57], 16, v2
	v_cmp_gt_u32_e64 s[58:59], 32, v2
	s_sub_i32 s18, 0, s2
	v_sub_u32_e32 v52, 0, v30
	s_lshl_b32 s19, s86, 6
	v_sub_u32_e32 v53, 0, v28
	v_lshlrev_b32_e32 v112, 2, v2
	v_add_u32_e32 v54, v8, v10
	v_lshlrev_b32_e32 v40, 1, v4
	v_add_u32_e32 v55, v11, v12
	v_add_u32_e32 v56, v13, v12
	v_add_u32_e32 v57, v6, v7
	s_and_saveexec_b64 s[2:3], s[44:45]
	s_cbranch_execz .Lmla_tab_done
	s_load_dwordx4 s[8:11], s[84:85], 0x48
	v_and_b32_e32 v0, 15, v2
	v_lshlrev_b32_e32 v0, 2, v0
	s_waitcnt lgkmcnt(0)
	global_load_dword v1, v0, s[8:9]
	global_load_dword v3, v0, s[10:11]
	v_add_u32_e32 v0, 0x22340, v0
	s_waitcnt vmcnt(0)
	ds_write_b32 v0, v1
	ds_write_b32 v0, v3 offset:64
	s_waitcnt lgkmcnt(0)
.Lmla_tab_done:
	s_or_b64 exec, exec, s[2:3]
	s_mov_b32 s6, s82
	s_branch .LBB0_735

.LBB0_735:
	s_and_saveexec_b64 s[2:3], s[44:45]
	s_cbranch_execz .LBB0_738
	s_mul_hi_i32 s7, s6, 0x78787879
	s_lshr_b32 s8, s7, 31
	s_ashr_i32 s7, s7, 5
	s_add_i32 s7, s7, s8
	s_bfe_u32 s12, s7, 0x20001
	s_lshl_b32 s7, s7, 2
	s_and_b32 s7, s7, 4
	s_or_b32 s7, s7, s12
	v_readlane_b32 s12, v254, 61
	s_or_b32 s34, s7, s12
	s_lshl_b32 s12, s34, 2
	s_add_u32 s8, s12, 0x22340
	v_mov_b32_e32 v0, s8
	ds_read_b32 v1, v0 offset:64
	ds_read_b32 v0, v0
	s_mov_b32 s7, 0xbfb8aa3b
	v_mov_b32_e32 v14, 0x7f800000
	s_mul_i32 s8, s6, 0x300
	s_add_u32 s8, s14, s8
	s_waitcnt vmcnt(0) lgkmcnt(0)
	v_lshlrev_b32_e32 v39, 16, v39
	v_lshlrev_b32_e32 v38, 16, v38
	v_add_f32_e32 v0, v39, v0
	v_add_f32_e32 v2, v38, v1
	v_mul_f32_e64 v3, |v2|, s7
	v_fma_f32 v4, |v2|, s7, -v3
	s_mov_b32 s7, 0xb2a5705f
	v_rndne_f32_e32 v5, v3
	v_fma_f32 v4, |v2|, s7, v4
	v_sub_f32_e32 v3, v3, v5
	v_add_f32_e32 v3, v3, v4
	v_exp_f32_e32 v3, v3
	v_cvt_i32_f32_e32 v4, v5
	s_mov_b32 s7, 0x42ce8ed0
	v_cmp_ngt_f32_e64 vcc, |v2|, s7
	s_mov_b32 s7, 0xc2b17218
	v_ldexp_f32 v3, v3, v4
	v_cndmask_b32_e32 v3, 0, v3, vcc
	v_cmp_nlt_f32_e64 vcc, |v2|, s7
	v_min_f32_e32 v1, 0, v2
	s_mov_b32 s7, 0x3f2aaaab
	v_cndmask_b32_e32 v2, v14, v3, vcc
	v_add_f32_e32 v3, 1.0, v2
	v_add_f32_e32 v4, -1.0, v3
	v_sub_f32_e32 v5, v4, v3
	v_add_f32_e32 v5, 1.0, v5
	v_sub_f32_e32 v4, v2, v4
	v_add_f32_e32 v6, v4, v5
	v_frexp_mant_f32_e32 v4, v3
	v_cmp_gt_f32_e32 vcc, s7, v4
	v_cvt_f64_f32_e32 v[4:5], v3
	v_frexp_exp_i32_f64_e32 v4, v[4:5]
	v_subbrev_co_u32_e32 v4, vcc, 0, v4, vcc
	v_sub_u32_e32 v5, 0, v4
	v_ldexp_f32 v3, v3, v5
	v_ldexp_f32 v5, v6, v5
	v_add_f32_e32 v6, -1.0, v3
	v_add_f32_e32 v7, 1.0, v6
	v_sub_f32_e32 v7, v3, v7
	v_add_f32_e32 v7, v5, v7
	v_add_f32_e32 v8, v6, v7
	v_sub_f32_e32 v6, v6, v8
	v_add_f32_e32 v6, v7, v6
	v_add_f32_e32 v7, 1.0, v3
	v_add_f32_e32 v9, -1.0, v7
	v_sub_f32_e32 v3, v3, v9
	v_add_f32_e32 v3, v5, v3
	v_add_f32_e32 v5, v7, v3
	v_sub_f32_e32 v7, v7, v5
	v_add_f32_e32 v3, v3, v7
	v_rcp_f32_e32 v7, v5
	v_cvt_f32_i32_e32 v4, v4
	s_mov_b32 s7, 0x3f317218
	v_mul_f32_e32 v9, v8, v7
	v_mul_f32_e32 v10, v5, v9
	v_fma_f32 v11, v9, v5, -v10
	v_fmac_f32_e32 v11, v9, v3
	v_add_f32_e32 v12, v10, v11
	v_sub_f32_e32 v13, v8, v12
	v_sub_f32_e32 v8, v8, v13
	v_sub_f32_e32 v10, v12, v10
	v_sub_f32_e32 v8, v8, v12
	v_add_f32_e32 v6, v6, v8
	v_sub_f32_e32 v8, v10, v11
	v_add_f32_e32 v6, v8, v6
	v_add_f32_e32 v8, v13, v6
	v_mul_f32_e32 v10, v7, v8
	v_mul_f32_e32 v11, v5, v10
	v_fma_f32 v5, v10, v5, -v11
	v_fmac_f32_e32 v5, v10, v3
	v_sub_f32_e32 v3, v13, v8
	v_add_f32_e32 v3, v6, v3
	v_add_f32_e32 v6, v11, v5
	v_sub_f32_e32 v12, v8, v6
	v_sub_f32_e32 v8, v8, v12
	v_sub_f32_e32 v11, v6, v11
	v_sub_f32_e32 v6, v8, v6
	v_add_f32_e32 v3, v3, v6
	v_sub_f32_e32 v5, v11, v5
	v_add_f32_e32 v3, v5, v3
	v_add_f32_e32 v5, v9, v10
	v_add_f32_e32 v3, v12, v3
	v_sub_f32_e32 v6, v5, v9
	v_mul_f32_e32 v3, v7, v3
	v_sub_f32_e32 v6, v10, v6
	v_add_f32_e32 v3, v6, v3
	v_mul_f32_e32 v9, 0x3f317218, v4
	v_add_f32_e32 v6, v5, v3
	v_fma_f32 v10, v4, s7, -v9
	v_mul_f32_e32 v7, v6, v6
	v_mov_b32_e32 v8, 0x3ecc95a3
	v_fmac_f32_e32 v10, 0xb102e308, v4
	v_sub_f32_e32 v4, v6, v5
	v_fmamk_f32 v8, v7, 0x3e9b6dac, v8
	v_sub_f32_e32 v3, v3, v4
	v_add_f32_e32 v4, v9, v10
	v_fmaak_f32 v8, v7, v8, 0x3f2aaada
	v_sub_f32_e32 v5, v4, v9
	v_ldexp_f32 v9, v6, 1
	v_mul_f32_e32 v6, v6, v7
	v_mul_f32_e32 v6, v6, v8
	v_add_f32_e32 v7, v9, v6
	v_sub_f32_e32 v8, v7, v9
	v_ldexp_f32 v3, v3, 1
	v_sub_f32_e32 v6, v6, v8
	v_add_f32_e32 v3, v3, v6
	v_add_f32_e32 v6, v7, v3
	v_sub_f32_e32 v7, v6, v7
	v_sub_f32_e32 v3, v3, v7
	v_add_f32_e32 v7, v4, v6
	v_sub_f32_e32 v8, v7, v4
	v_sub_f32_e32 v9, v7, v8
	v_sub_f32_e32 v5, v10, v5
	v_sub_f32_e32 v4, v4, v9
	v_sub_f32_e32 v6, v6, v8
	v_add_f32_e32 v4, v6, v4
	v_add_f32_e32 v6, v5, v3
	v_sub_f32_e32 v8, v6, v5
	v_sub_f32_e32 v9, v6, v8
	v_sub_f32_e32 v5, v5, v9
	v_sub_f32_e32 v3, v3, v8
	v_add_f32_e32 v4, v6, v4
	v_add_f32_e32 v3, v3, v5
	v_add_f32_e32 v5, v7, v4
	v_sub_f32_e32 v6, v5, v7
	v_sub_f32_e32 v4, v4, v6
	v_add_f32_e32 v3, v3, v4
	s_mov_b32 s7, 0x7f800000
	v_add_f32_e32 v3, v5, v3
	v_cmp_neq_f32_e32 vcc, s7, v2
	s_mov_b32 s7, 0x33800000
	s_nop 0
	v_cndmask_b32_e32 v3, v14, v3, vcc
	v_cmp_lt_f32_e64 vcc, |v2|, s7
	s_mul_hi_i32 s7, s6, 0x300
	s_addc_u32 s9, s15, s7
	v_cndmask_b32_e32 v2, v3, v2, vcc
	v_sub_f32_e32 v1, v1, v2
	v_mov_b32_e32 v2, v1
	s_nop 1
	v_add_f32_dpp v2, v2, v2 row_shr:1 row_mask:0xf bank_mask:0xf
	s_nop 1
	v_add_f32_dpp v2, v2, v2 row_shr:2 row_mask:0xf bank_mask:0xf
	s_nop 1
	v_add_f32_dpp v2, v2, v2 row_shr:4 row_mask:0xf bank_mask:0xf
	s_nop 1
	v_add_f32_dpp v2, v2, v2 row_shr:8 row_mask:0xf bank_mask:0xf
	s_nop 1
	v_add_f32_dpp v2, v2, v2 row_bcast:15 row_mask:0xa bank_mask:0xf
	s_nop 1
	v_add_f32_dpp v2, v2, v2 row_bcast:31 row_mask:0xc bank_mask:0xf
	s_nop 1
	v_sub_f32_e32 v3, v0, v2
	v_mov_b32_e32 v4, v3
	s_nop 1
	v_max_f32_dpp v4, v4, v4 row_shr:1 row_mask:0xf bank_mask:0xf
	s_nop 1
	v_max_f32_dpp v4, v4, v4 row_shr:2 row_mask:0xf bank_mask:0xf
	s_nop 1
	v_max_f32_dpp v4, v4, v4 row_shr:4 row_mask:0xf bank_mask:0xf
	s_nop 1
	v_max_f32_dpp v4, v4, v4 row_shr:8 row_mask:0xf bank_mask:0xf
	s_nop 1
	v_max_f32_dpp v4, v4, v4 row_bcast:15 row_mask:0xa bank_mask:0xf
	s_nop 1
	v_max_f32_dpp v4, v4, v4 row_bcast:31 row_mask:0xc bank_mask:0xf
	s_nop 1
	v_lshl_add_u64 v[0:1], s[8:9], 0, v[112:113]
	global_store_dword v[0:1], v3, off
	v_lshl_add_u64 v[0:1], v[28:29], 2, s[8:9]
	v_readlane_b32 s8, v2, 63
	v_readlane_b32 s9, v4, 63
	global_store_dword v[0:1], v2, off offset:256
	global_store_dword v[0:1], v4, off offset:512
	ds_write_b32 v42, v3 offset:64512
	s_and_b64 exec, exec, s[46:47]
	s_cbranch_execz .LBB0_738
	s_ashr_i32 s7, s6, 31
	s_lshl_b64 s[10:11], s[6:7], 3
	s_add_u32 s10, s16, s10
	v_readlane_b32 s7, v254, 33
	s_addc_u32 s11, s17, s11
	v_mov_b32_e32 v1, s9
	v_mov_b32_e32 v0, s7
	ds_write_b32 v0, v1
	v_mov_b32_e32 v0, s8
	v_mov_b64_e32 v[2:3], s[10:11]
	global_store_dwordx2 v[2:3], v[0:1], off
